# baseline (speedup 1.0000x reference)
; __device__ __forceinline__ float bflo(unsigned w) { return __uint_as_float(w << 16); }
; __device__ __forceinline__ float bfhi(unsigned w) { return __uint_as_float(w & 0xffff0000u); }
; #define PSEL(QA, R) (__builtin_amdgcn_readfirstlane(sel[(QA) * 512 + (R)]))
; #define PLOAD8(QA, BASE, BLK) { unsigned off_ = loff; asm volatile("" : "+v"(off_)); const char* cb_ = (BASE) + (long)(BLK) * 4096; \
;       _Pragma("unroll") for (int i_ = 0; i_ < 4; ++i_) kvb[QA][i_] = *(const l64x2*)(cb_ + i_ * 1024 + off_); }
; __device__ __forceinline__ void nsa_quad(const Params& p, int qd, int g, float* slds, const int lane_in) {
;     ...
;     if (npriv > 0) {
;       typedef long l64x2 __attribute__((ext_vector_type(2)));
;       l64x2 kvb[4][4];
;       const char* ks8 = (const char*)(p.ws + OFF_ks8) + (long)g * 256 * 4096;
;       const char* vs8 = (const char*)(p.ws + OFF_vs8) + (long)g * 256 * 4096;
;       long q8_0, q8_1;
;       {
;         const u32x4 qa_ = __builtin_bit_cast(u32x4, qst[0]), qb_ = __builtin_bit_cast(u32x4, qst[64]);
;         const unsigned a0 = pack_fp8x4(bflo(qa_[0]), bfhi(qa_[0]), bflo(qa_[1]), bfhi(qa_[1]));
;         const unsigned a1 = pack_fp8x4(bflo(qa_[2]), bfhi(qa_[2]), bflo(qa_[3]), bfhi(qa_[3]));
;         const unsigned b0 = pack_fp8x4(bflo(qb_[0]), bfhi(qb_[0]), bflo(qb_[1]), bfhi(qb_[1]));
;         const unsigned b1 = pack_fp8x4(bflo(qb_[2]), bfhi(qb_[2]), bflo(qb_[3]), bfhi(qb_[3]));
;         q8_0 = (long)(((unsigned long long)a1 << 32) | (unsigned long long)a0);
;         q8_1 = (long)(((unsigned long long)b1 << 32) | (unsigned long long)b0);
;       }
;     ...
; #pragma unroll
;       for (int qa = 0; qa < 4; ++qa) { const int blk = PSEL(qa, 0); PLOAD8(qa, ks8, blk) }
; #pragma unroll
;       for (int dt = 0; dt < 4; ++dt) oacc[dt] *= 256.f;
.LBB0_711:
	v_readlane_b32 s0, v255, 57
	v_readlane_b32 s1, v255, 58
	s_sub_i32 s0, s0, s1
	s_min_i32 s12, s0, s91
	s_cmp_lt_i32 s12, 1
	s_cbranch_scc1 .LBB0_726
	v_mov_b32_e32 v0, s76
	s_waitcnt vmcnt(0)
	ds_read_b32 v68, v0
	s_waitcnt lgkmcnt(2)
	ds_read_b128 v[148:151], v2 offset:12288
	s_waitcnt lgkmcnt(2)
	ds_read_b128 v[152:155], v2 offset:13312
	v_mov_b32_e32 v69, v164
	s_waitcnt lgkmcnt(2)
	v_readfirstlane_b32 s0, v68
	ds_read_b32 v84, v0 offset:2048
	s_ashr_i32 s1, s0, 31
	s_nop 0
	v_writelane_b32 v255, s0, 59
	s_lshl_b64 s[0:1], s[0:1], 12
	s_add_u32 s0, s77, s0
	s_addc_u32 s1, s94, s1
	global_load_dwordx4 v[80:83], v69, s[0:1]
	global_load_dwordx4 v[76:79], v69, s[0:1] offset:1024
	global_load_dwordx4 v[72:75], v69, s[0:1] offset:2048
	s_nop 0
	global_load_dwordx4 v[68:71], v69, s[0:1] offset:3072
	s_waitcnt lgkmcnt(0)
	v_readfirstlane_b32 s0, v84
	v_mov_b32_e32 v84, v164
	ds_read_b32 v116, v0 offset:4096
	s_ashr_i32 s1, s0, 31
	s_nop 0
	v_writelane_b32 v255, s0, 60
	s_lshl_b64 s[0:1], s[0:1], 12
	s_add_u32 s0, s77, s0
	s_addc_u32 s1, s94, s1
	global_load_dwordx4 v[96:99], v84, s[0:1]
	global_load_dwordx4 v[92:95], v84, s[0:1] offset:1024
	global_load_dwordx4 v[88:91], v84, s[0:1] offset:2048
	s_nop 0
	global_load_dwordx4 v[84:87], v84, s[0:1] offset:3072
	s_waitcnt lgkmcnt(0)
	v_readfirstlane_b32 s0, v116
	v_mov_b32_e32 v116, v164
	ds_read_b32 v0, v0 offset:6144
	s_ashr_i32 s1, s0, 31
	s_nop 0
	v_writelane_b32 v255, s0, 61
	s_lshl_b64 s[0:1], s[0:1], 12
	s_add_u32 s0, s77, s0
	s_addc_u32 s1, s94, s1
	global_load_dwordx4 v[128:131], v116, s[0:1]
	global_load_dwordx4 v[124:127], v116, s[0:1] offset:1024
	global_load_dwordx4 v[120:123], v116, s[0:1] offset:2048
	s_nop 0
	global_load_dwordx4 v[116:119], v116, s[0:1] offset:3072
	s_waitcnt lgkmcnt(0)
	v_readfirstlane_b32 s0, v0
	s_ashr_i32 s1, s0, 31
	s_nop 0
	v_writelane_b32 v255, s0, 62
	s_lshl_b64 s[0:1], s[0:1], 12
	v_mov_b32_e32 v0, v164
	s_add_u32 s0, s77, s0
	s_addc_u32 s1, s94, s1
	global_load_dwordx4 v[132:135], v0, s[0:1] offset:3072
	global_load_dwordx4 v[136:139], v0, s[0:1] offset:2048
	global_load_dwordx4 v[140:143], v0, s[0:1] offset:1024
	global_load_dwordx4 v[144:147], v0, s[0:1]
	v_lshlrev_b32_e32 v0, 16, v148
	v_and_b32_e32 v148, 0xffff0000, v148
	v_mov_b32_e32 v162, v1
	v_cvt_pk_fp8_f32 v162, v0, v148
	v_lshlrev_b32_e32 v0, 16, v150
	v_and_b32_e32 v148, 0xffff0000, v150
	v_mov_b32_e32 v161, v1
	v_cvt_pk_fp8_f32 v161, v0, v148
	v_lshlrev_b32_e32 v0, 16, v151
	v_and_b32_e32 v148, 0xffff0000, v151
	v_mov_b32_e32 v168, v1
	v_cvt_pk_fp8_f32 v161, v0, v148 op_sel:[0,0,1]
	v_lshlrev_b32_e32 v0, 16, v152
	v_and_b32_e32 v148, 0xffff0000, v152
	v_cvt_pk_fp8_f32 v168, v0, v148
	v_lshlrev_b32_e32 v0, 16, v154
	v_and_b32_e32 v148, 0xffff0000, v154
	v_mov_b32_e32 v163, v1
	v_cvt_pk_fp8_f32 v163, v0, v148
	v_lshlrev_b32_e32 v156, 16, v149
	v_and_b32_e32 v149, 0xffff0000, v149
	v_cvt_pk_fp8_f32 v162, v156, v149 op_sel:[0,0,1]
	v_lshlrev_b32_e32 v149, 16, v153
	v_and_b32_e32 v150, 0xffff0000, v153
	v_lshlrev_b32_e32 v0, 16, v155
	v_and_b32_e32 v148, 0xffff0000, v155
	v_cvt_pk_fp8_f32 v168, v149, v150 op_sel:[0,0,1]
	v_cvt_pk_fp8_f32 v163, v0, v148 op_sel:[0,0,1]
	s_mov_b32 s0, 0x43800000
	v_mul_f32_e32 v114, s0, v114
	v_mul_f32_e32 v115, s0, v115
	v_mul_f32_e32 v112, s0, v112
	v_mul_f32_e32 v113, s0, v113
	v_mul_f32_e32 v110, s0, v110
	v_mul_f32_e32 v111, s0, v111
	v_mul_f32_e32 v108, s0, v108
	v_mul_f32_e32 v109, s0, v109
	v_mul_f32_e32 v106, s0, v106
	v_mul_f32_e32 v107, s0, v107
	v_mul_f32_e32 v104, s0, v104
	v_mul_f32_e32 v105, s0, v105
	v_mul_f32_e32 v102, s0, v102
	v_mul_f32_e32 v103, s0, v103
	v_mul_f32_e32 v100, s0, v100
	v_mul_f32_e32 v101, s0, v101
	v_cmp_eq_u32_e64 s[0:1], 0, v160
	v_cmp_eq_u32_e64 s[2:3], 1, v160
	v_cmp_eq_u32_e64 s[4:5], 2, v160
	v_cmp_eq_u32_e64 s[6:7], 3, v160
	v_cndmask_b32_e64 v149, 0, v161, s[0:1]
	v_cndmask_b32_e64 v148, 0, v162, s[0:1]
	v_cndmask_b32_e64 v151, 0, v163, s[0:1]
	v_cndmask_b32_e64 v150, 0, v168, s[0:1]
	v_cndmask_b32_e64 v153, 0, v161, s[2:3]
	v_cndmask_b32_e64 v152, 0, v162, s[2:3]
	v_cndmask_b32_e64 v155, 0, v163, s[2:3]
	v_cndmask_b32_e64 v154, 0, v168, s[2:3]
	v_cndmask_b32_e64 v157, 0, v161, s[4:5]
	v_cndmask_b32_e64 v156, 0, v162, s[4:5]
	v_cndmask_b32_e64 v159, 0, v163, s[4:5]
	v_cndmask_b32_e64 v158, 0, v168, s[4:5]
	v_cndmask_b32_e64 v161, 0, v161, s[6:7]
	v_cndmask_b32_e64 v160, 0, v162, s[6:7]
	v_cndmask_b32_e64 v163, 0, v163, s[6:7]
	v_cndmask_b32_e64 v162, 0, v168, s[6:7]
	s_mov_b32 s13, 0
	s_mov_b32 s14, s76
	v_readlane_b32 s88, v253, 37
	v_readlane_b32 s89, v253, 38
	v_readlane_b32 s91, v255, 54
; #define PSEL(QA, R) (__builtin_amdgcn_readfirstlane(sel[(QA) * 512 + (R)]))
; #define PLOAD8(QA, BASE, BLK) { unsigned off_ = loff; asm volatile("" : "+v"(off_)); const char* cb_ = (BASE) + (long)(BLK) * 4096; \
;       _Pragma("unroll") for (int i_ = 0; i_ < 4; ++i_) kvb[QA][i_] = *(const l64x2*)(cb_ + i_ * 1024 + off_); }
; __device__ __forceinline__ void nsa_quad(const Params& p, int qd, int g, float* slds, const int lane_in) {
;     ...
;       for (int r = 0; r < npriv; ++r) {
;         f32x4 sc[4];
; #pragma unroll
;         for (int tile = 0; tile < 4; ++tile) sc[tile] = f32x4{0.f, 0.f, 0.f, 0.f};
; #pragma unroll
;         for (int qa = 0; qa < 4; ++qa) {
;           const bool mine = (qi == qa);
;           const long qm0 = mine ? q8_0 : 0L, qm1 = mine ? q8_1 : 0L;
; #pragma unroll
;           for (int tile = 0; tile < 4; ++tile) {
;             sc[tile] = __builtin_amdgcn_mfma_f32_16x16x32_fp8_fp8(kvb[qa][tile][0], qm0, sc[tile], 0, 0, 0);
;             sc[tile] = __builtin_amdgcn_mfma_f32_16x16x32_fp8_fp8(kvb[qa][tile][1], qm1, sc[tile], 0, 0, 0);
;           }
;           const int blk = PSEL(qa, r);
;           __builtin_amdgcn_sched_barrier(0);
;           PLOAD8(qa, vs8, blk)
;           __builtin_amdgcn_sched_barrier(0);
;         }
;         float cm = NEGF;
; #pragma unroll
;         for (int tile = 0; tile < 4; ++tile)
; #pragma unroll
;           for (int j = 0; j < 4; ++j) cm = fmaxf(cm, sc[tile][j]);
;         cm = rows_max(cm);
;         const float mn = fmaxf(m, cm * SC_LOG2);
;         const float alpha = __builtin_amdgcn_exp2f(m - mn);
;         float ls = 0.f;
; #pragma unroll
;         for (int tile = 0; tile < 4; ++tile)
; #pragma unroll
;           for (int j = 0; j < 4; ++j) { const float pp = __builtin_amdgcn_exp2f(__builtin_fmaf(sc[tile][j], SC_LOG2, -mn)); sc[tile][j] = pp; ls += pp; }
.LBB0_713:
	s_waitcnt vmcnt(15)
	v_mfma_f32_16x16x32_fp8_fp8 v[168:171], v[80:81], v[148:149], 0
	v_mov_b32_e32 v0, s14
	v_mfma_f32_16x16x32_fp8_fp8 v[168:171], v[82:83], v[150:151], v[168:171]
	s_waitcnt vmcnt(14)
	v_mfma_f32_16x16x32_fp8_fp8 v[80:83], v[76:77], v[148:149], 0
	v_mfma_f32_16x16x32_fp8_fp8 v[172:175], v[78:79], v[150:151], v[80:83]
	s_waitcnt vmcnt(13)
	v_mfma_f32_16x16x32_fp8_fp8 v[76:79], v[72:73], v[148:149], 0
	v_mfma_f32_16x16x32_fp8_fp8 v[176:179], v[74:75], v[150:151], v[76:79]
	s_waitcnt vmcnt(12)
	v_mfma_f32_16x16x32_fp8_fp8 v[72:75], v[68:69], v[148:149], 0
	v_readlane_b32 s8, v255, 59
	v_mfma_f32_16x16x32_fp8_fp8 v[180:183], v[70:71], v[150:151], v[72:75]
	s_ashr_i32 s9, s8, 31
	s_lshl_b64 s[8:9], s[8:9], 12
	v_mov_b32_e32 v68, v164
	s_add_u32 s8, s95, s8
	s_addc_u32 s9, s51, s9
	global_load_dwordx4 v[80:83], v68, s[8:9]
	global_load_dwordx4 v[76:79], v68, s[8:9] offset:1024
	global_load_dwordx4 v[72:75], v68, s[8:9] offset:2048
	s_nop 0
	global_load_dwordx4 v[68:71], v68, s[8:9] offset:3072
	s_waitcnt vmcnt(15)
	v_mfma_f32_16x16x32_fp8_fp8 v[168:171], v[96:97], v[152:153], v[168:171]
	v_mfma_f32_16x16x32_fp8_fp8 v[168:171], v[98:99], v[154:155], v[168:171]
	s_waitcnt vmcnt(14)
	v_mfma_f32_16x16x32_fp8_fp8 v[96:99], v[92:93], v[152:153], v[172:175]
	v_mfma_f32_16x16x32_fp8_fp8 v[172:175], v[94:95], v[154:155], v[96:99]
	s_waitcnt vmcnt(13)
	v_mfma_f32_16x16x32_fp8_fp8 v[92:95], v[88:89], v[152:153], v[176:179]
	v_mfma_f32_16x16x32_fp8_fp8 v[176:179], v[90:91], v[154:155], v[92:95]
	s_waitcnt vmcnt(12)
	v_mfma_f32_16x16x32_fp8_fp8 v[88:91], v[84:85], v[152:153], v[180:183]
	v_readlane_b32 s8, v255, 60
	v_mfma_f32_16x16x32_fp8_fp8 v[180:183], v[86:87], v[154:155], v[88:91]
	s_ashr_i32 s9, s8, 31
	s_lshl_b64 s[8:9], s[8:9], 12
	v_mov_b32_e32 v84, v164
	s_add_u32 s8, s95, s8
	s_addc_u32 s9, s51, s9
	global_load_dwordx4 v[96:99], v84, s[8:9]
	global_load_dwordx4 v[92:95], v84, s[8:9] offset:1024
	global_load_dwordx4 v[88:91], v84, s[8:9] offset:2048
	s_nop 0
	global_load_dwordx4 v[84:87], v84, s[8:9] offset:3072
	s_waitcnt vmcnt(15)
	v_mfma_f32_16x16x32_fp8_fp8 v[168:171], v[128:129], v[156:157], v[168:171]
	v_mfma_f32_16x16x32_fp8_fp8 v[168:171], v[130:131], v[158:159], v[168:171]
	s_waitcnt vmcnt(14)
	v_mfma_f32_16x16x32_fp8_fp8 v[128:131], v[124:125], v[156:157], v[172:175]
	v_mfma_f32_16x16x32_fp8_fp8 v[172:175], v[126:127], v[158:159], v[128:131]
	s_waitcnt vmcnt(13)
	v_mfma_f32_16x16x32_fp8_fp8 v[124:127], v[120:121], v[156:157], v[176:179]
	v_mfma_f32_16x16x32_fp8_fp8 v[176:179], v[122:123], v[158:159], v[124:127]
	s_waitcnt vmcnt(12)
	v_mfma_f32_16x16x32_fp8_fp8 v[120:123], v[116:117], v[156:157], v[180:183]
	v_readlane_b32 s8, v255, 61
	v_mfma_f32_16x16x32_fp8_fp8 v[180:183], v[118:119], v[158:159], v[120:123]
	s_ashr_i32 s9, s8, 31
	s_lshl_b64 s[8:9], s[8:9], 12
	v_mov_b32_e32 v116, v164
	s_add_u32 s8, s95, s8
	s_addc_u32 s9, s51, s9
	global_load_dwordx4 v[128:131], v116, s[8:9]
	global_load_dwordx4 v[124:127], v116, s[8:9] offset:1024
	global_load_dwordx4 v[120:123], v116, s[8:9] offset:2048
	s_nop 0
	global_load_dwordx4 v[116:119], v116, s[8:9] offset:3072
	s_waitcnt vmcnt(12)
	v_mfma_f32_16x16x32_fp8_fp8 v[168:171], v[144:145], v[160:161], v[168:171]
	v_readlane_b32 s8, v255, 62
	v_mfma_f32_16x16x32_fp8_fp8 v[168:171], v[146:147], v[162:163], v[168:171]
	v_mfma_f32_16x16x32_fp8_fp8 v[144:147], v[140:141], v[160:161], v[172:175]
	v_mfma_f32_16x16x32_fp8_fp8 v[172:175], v[142:143], v[162:163], v[144:147]
	v_mfma_f32_16x16x32_fp8_fp8 v[140:143], v[136:137], v[160:161], v[176:179]
	v_mfma_f32_16x16x32_fp8_fp8 v[176:179], v[138:139], v[162:163], v[140:143]
	v_mfma_f32_16x16x32_fp8_fp8 v[136:139], v[132:133], v[160:161], v[180:183]
	v_mfma_f32_16x16x32_fp8_fp8 v[180:183], v[134:135], v[162:163], v[136:139]
	s_ashr_i32 s9, s8, 31
	s_lshl_b64 s[8:9], s[8:9], 12
	v_mov_b32_e32 v0, v164
	s_add_u32 s8, s95, s8
	s_addc_u32 s9, s51, s9
	global_load_dwordx4 v[144:147], v0, s[8:9]
	global_load_dwordx4 v[140:143], v0, s[8:9] offset:1024
	global_load_dwordx4 v[136:139], v0, s[8:9] offset:2048
	global_load_dwordx4 v[132:135], v0, s[8:9] offset:3072
	v_max3_f32 v0, v168, s37, v169
	v_max3_f32 v0, v0, v170, v171
	v_max3_f32 v0, v0, v172, v173
	v_max3_f32 v0, v0, v174, v175
	v_max3_f32 v0, v0, v176, v177
	v_max3_f32 v0, v0, v178, v179
	v_max3_f32 v0, v0, v180, v181
	v_max3_f32 v0, v0, v182, v183
	v_mov_b32_e32 v184, v0
	s_nop 1
	v_permlane16_swap_b32_e32 v0, v184
	v_max_f32_e32 v184, v184, v184
	v_max_f32_e32 v0, v0, v0
	v_max_f32_e32 v0, v0, v184
	v_mov_b32_e32 v184, v0
	s_nop 1
	v_permlane32_swap_b32_e32 v0, v184
	v_max_f32_e32 v184, v184, v184
	v_max_f32_e32 v0, v0, v0
	v_max_f32_e32 v0, v0, v184
	v_mov_b32_e32 v184, v166
	v_mul_f32_e32 v0, 0x3e38aa3b, v0
	v_max_f32_e32 v166, v184, v184
	v_max_f32_e32 v166, v166, v0
	v_fma_f32 v0, v168, s49, -v166
	v_exp_f32_e32 v168, v0
	v_fma_f32 v169, v169, s49, -v166
	v_exp_f32_e32 v169, v169
	v_fma_f32 v170, v170, s49, -v166
	v_exp_f32_e32 v170, v170
	v_fma_f32 v171, v171, s49, -v166
	v_exp_f32_e32 v171, v171
	v_fma_f32 v172, v172, s49, -v166
	v_sub_f32_e32 v0, v184, v166
	v_add_f32_e32 v184, 0, v168
	v_exp_f32_e32 v172, v172
	v_fma_f32 v173, v173, s49, -v166
	v_add_f32_e32 v184, v169, v184
	v_exp_f32_e32 v173, v173
	v_add_f32_e32 v184, v170, v184
	v_add_f32_e32 v184, v171, v184
	v_add_f32_e32 v184, v172, v184
	v_fma_f32 v174, v174, s49, -v166
	v_fma_f32 v175, v175, s49, -v166
	v_mul_f32_e32 v185, 0x43800000, v168
	v_mul_f32_e32 v169, 0x43800000, v169
	v_mov_b32_e32 v168, v1
	v_exp_f32_e32 v174, v174
	v_exp_f32_e32 v175, v175
	v_fma_f32 v176, v176, s49, -v166
	v_add_f32_e32 v184, v173, v184
; #define PSEL(QA, R) (__builtin_amdgcn_readfirstlane(sel[(QA) * 512 + (R)]))
; #define PLOAD8(QA, BASE, BLK) { unsigned off_ = loff; asm volatile("" : "+v"(off_)); const char* cb_ = (BASE) + (long)(BLK) * 4096; \
;       _Pragma("unroll") for (int i_ = 0; i_ < 4; ++i_) kvb[QA][i_] = *(const l64x2*)(cb_ + i_ * 1024 + off_); }
; __device__ __forceinline__ void nsa_quad(const Params& p, int qd, int g, float* slds, const int lane_in) {
;     ...
;         const float mn = fmaxf(m, cm * SC_LOG2);
;         const float alpha = __builtin_amdgcn_exp2f(m - mn);
;         float ls = 0.f;
; #pragma unroll
;         for (int tile = 0; tile < 4; ++tile)
; #pragma unroll
;           for (int j = 0; j < 4; ++j) { const float pp = __builtin_amdgcn_exp2f(__builtin_fmaf(sc[tile][j], SC_LOG2, -mn)); sc[tile][j] = pp; ls += pp; }
;         ls = rows_sum(ls);
;         l = l * alpha + ls;
;         m = mn;
; #pragma unroll
;         for (int dt = 0; dt < 4; ++dt) oacc[dt] *= alpha;
;         unsigned pu[2][2];
; #pragma unroll
;         for (int s2 = 0; s2 < 2; ++s2) {
;           pu[s2][0] = pack_fp8x4(sc[2 * s2][0] * 256.f, sc[2 * s2][1] * 256.f, sc[2 * s2][2] * 256.f, sc[2 * s2][3] * 256.f);
;           pu[s2][1] = pack_fp8x4(sc[2 * s2 + 1][0] * 256.f, sc[2 * s2 + 1][1] * 256.f, sc[2 * s2 + 1][2] * 256.f,
;                                  sc[2 * s2 + 1][3] * 256.f);
;         }
; #pragma unroll
;         for (int qa = 0; qa < 4; ++qa) {
;           const bool mine = (qi == qa);
; #pragma unroll
;           for (int s2 = 0; s2 < 2; ++s2) {
;             const unsigned plo = mine ? pu[s2][0] : 0u, phi = mine ? pu[s2][1] : 0u;
;             const long pm = (long)(((unsigned long long)phi << 32) | (unsigned long long)plo);
; #pragma unroll
;             for (int dt = 0; dt < 4; ++dt)
;               oacc[dt] = __builtin_amdgcn_mfma_f32_16x16x32_fp8_fp8(kvb[qa][dt][s2], pm, oacc[dt], 0, 0, 0);
;           }
;           __builtin_amdgcn_sched_barrier(0);
;           if (r + 1 < npriv) { const int blk = PSEL(qa, r + 1); PLOAD8(qa, ks8, blk) }
	v_fma_f32 v177, v177, s49, -v166
	v_cvt_pk_fp8_f32 v168, v185, v169
	v_mul_f32_e32 v169, 0x43800000, v172
	v_mul_f32_e32 v173, 0x43800000, v173
	v_mov_b32_e32 v172, v1
	v_exp_f32_e32 v176, v176
	v_exp_f32_e32 v177, v177
	v_cvt_pk_fp8_f32 v172, v169, v173
	v_mul_f32_e32 v170, 0x43800000, v170
	v_mul_f32_e32 v171, 0x43800000, v171
	v_fma_f32 v178, v178, s49, -v166
	v_fma_f32 v179, v179, s49, -v166
	v_cvt_pk_fp8_f32 v168, v170, v171 op_sel:[0,0,1]
	v_mul_f32_e32 v169, 0x43800000, v174
	v_mul_f32_e32 v170, 0x43800000, v175
	v_exp_f32_e32 v178, v178
	v_exp_f32_e32 v179, v179
	v_fma_f32 v180, v180, s49, -v166
	v_fma_f32 v181, v181, s49, -v166
	v_cvt_pk_fp8_f32 v172, v169, v170 op_sel:[0,0,1]
	v_mul_f32_e32 v169, 0x43800000, v176
	v_mul_f32_e32 v170, 0x43800000, v177
	v_mov_b32_e32 v171, v1
	v_exp_f32_e32 v180, v180
	v_exp_f32_e32 v181, v181
	v_cvt_pk_fp8_f32 v171, v169, v170
	v_add_f32_e32 v184, v174, v184
	v_fma_f32 v182, v182, s49, -v166
	v_fma_f32 v183, v183, s49, -v166
	v_mul_f32_e32 v173, 0x43800000, v178
	v_mul_f32_e32 v169, 0x43800000, v179
	v_add_f32_e32 v184, v175, v184
	v_exp_f32_e32 v182, v182
	v_exp_f32_e32 v183, v183
	v_cvt_pk_fp8_f32 v171, v173, v169 op_sel:[0,0,1]
	v_mul_f32_e32 v169, 0x43800000, v180
	v_mul_f32_e32 v170, 0x43800000, v181
	v_mov_b32_e32 v173, v1
	v_add_f32_e32 v184, v176, v184
	v_exp_f32_e32 v0, v0
	v_cvt_pk_fp8_f32 v173, v169, v170
	v_add_f32_e32 v184, v177, v184
	v_add_f32_e32 v184, v178, v184
	v_add_f32_e32 v184, v179, v184
	v_mul_f32_e32 v169, 0x43800000, v182
	v_mul_f32_e32 v170, 0x43800000, v183
	v_add_f32_e32 v184, v180, v184
	v_mul_f32_e32 v102, v0, v102
	v_mul_f32_e32 v103, v0, v103
	v_mul_f32_e32 v100, v0, v100
	v_mul_f32_e32 v101, v0, v101
	v_mul_f32_e32 v106, v0, v106
	v_mul_f32_e32 v107, v0, v107
	v_mul_f32_e32 v104, v0, v104
	v_mul_f32_e32 v105, v0, v105
	v_mul_f32_e32 v110, v0, v110
	v_mul_f32_e32 v111, v0, v111
	v_mul_f32_e32 v108, v0, v108
	v_mul_f32_e32 v109, v0, v109
	v_mul_f32_e32 v114, v0, v114
	v_mul_f32_e32 v115, v0, v115
	v_mul_f32_e32 v112, v0, v112
	v_mul_f32_e32 v113, v0, v113
	v_cndmask_b32_e64 v174, 0, v168, s[0:1]
	v_cndmask_b32_e64 v175, 0, v172, s[0:1]
	v_cvt_pk_fp8_f32 v173, v169, v170 op_sel:[0,0,1]
	v_add_f32_e32 v184, v181, v184
	s_waitcnt vmcnt(15)
	v_mfma_f32_16x16x32_fp8_fp8 v[100:103], v[80:81], v[174:175], v[100:103]
	v_add_f32_e32 v184, v182, v184
	v_add_f32_e32 v184, v183, v184
	v_mov_b32_e32 v169, v184
	s_waitcnt vmcnt(14)
	v_mfma_f32_16x16x32_fp8_fp8 v[104:107], v[76:77], v[174:175], v[104:107]
	v_permlane16_swap_b32_e32 v184, v169
	v_add_f32_e32 v169, v184, v169
	s_waitcnt vmcnt(13)
	v_mfma_f32_16x16x32_fp8_fp8 v[108:111], v[72:73], v[174:175], v[108:111]
	s_add_i32 s13, s13, 1
	v_mov_b32_e32 v170, v169
	s_cmp_lt_i32 s13, s12
	s_waitcnt vmcnt(12)
	v_mfma_f32_16x16x32_fp8_fp8 v[112:115], v[68:69], v[174:175], v[112:115]
	v_cndmask_b32_e64 v174, 0, v171, s[0:1]
	v_cndmask_b32_e64 v175, 0, v173, s[0:1]
	v_permlane32_swap_b32_e32 v169, v170
	s_nop 0
	v_mfma_f32_16x16x32_fp8_fp8 v[100:103], v[82:83], v[174:175], v[100:103]
	s_cselect_b64 s[10:11], -1, 0
	s_cmp_ge_i32 s13, s12
	v_mfma_f32_16x16x32_fp8_fp8 v[104:107], v[78:79], v[174:175], v[104:107]
	v_mfma_f32_16x16x32_fp8_fp8 v[108:111], v[74:75], v[174:175], v[108:111]
	v_mfma_f32_16x16x32_fp8_fp8 v[112:115], v[70:71], v[174:175], v[112:115]
	s_cbranch_scc1 .LBB0_715
	v_mov_b32_e32 v68, s14
	ds_read_b32 v68, v68 offset:4
	v_mov_b32_e32 v69, v164
	s_waitcnt lgkmcnt(0)
	v_readfirstlane_b32 s8, v68
	s_ashr_i32 s9, s8, 31
	s_nop 0
	v_writelane_b32 v255, s8, 59
	s_lshl_b64 s[8:9], s[8:9], 12
	s_add_u32 s8, s77, s8
	s_addc_u32 s9, s94, s9
	s_nop 0
	global_load_dwordx4 v[80:83], v69, s[8:9]
	global_load_dwordx4 v[76:79], v69, s[8:9] offset:1024
	global_load_dwordx4 v[72:75], v69, s[8:9] offset:2048
	s_nop 0
	global_load_dwordx4 v[68:71], v69, s[8:9] offset:3072
; #define PSEL(QA, R) (__builtin_amdgcn_readfirstlane(sel[(QA) * 512 + (R)]))
; #define PLOAD8(QA, BASE, BLK) { unsigned off_ = loff; asm volatile("" : "+v"(off_)); const char* cb_ = (BASE) + (long)(BLK) * 4096; \
;       _Pragma("unroll") for (int i_ = 0; i_ < 4; ++i_) kvb[QA][i_] = *(const l64x2*)(cb_ + i_ * 1024 + off_); }
; __device__ __forceinline__ void nsa_quad(const Params& p, int qd, int g, float* slds, const int lane_in) {
;     ...
; #pragma unroll
;         for (int qa = 0; qa < 4; ++qa) {
;           const bool mine = (qi == qa);
; #pragma unroll
;           for (int s2 = 0; s2 < 2; ++s2) {
;             const unsigned plo = mine ? pu[s2][0] : 0u, phi = mine ? pu[s2][1] : 0u;
;             const long pm = (long)(((unsigned long long)phi << 32) | (unsigned long long)plo);
; #pragma unroll
;             for (int dt = 0; dt < 4; ++dt)
;               oacc[dt] = __builtin_amdgcn_mfma_f32_16x16x32_fp8_fp8(kvb[qa][dt][s2], pm, oacc[dt], 0, 0, 0);
;           }
;           __builtin_amdgcn_sched_barrier(0);
;           if (r + 1 < npriv) { const int blk = PSEL(qa, r + 1); PLOAD8(qa, ks8, blk) }
;           __builtin_amdgcn_sched_barrier(0);
;         }
.LBB0_715:
	v_cndmask_b32_e64 v174, 0, v168, s[2:3]
	v_cndmask_b32_e64 v175, 0, v172, s[2:3]
	s_waitcnt vmcnt(11)
	s_nop 0
	v_mfma_f32_16x16x32_fp8_fp8 v[100:103], v[96:97], v[174:175], v[100:103]
	s_waitcnt vmcnt(10)
	v_mfma_f32_16x16x32_fp8_fp8 v[104:107], v[92:93], v[174:175], v[104:107]
	s_waitcnt vmcnt(9)
	v_mfma_f32_16x16x32_fp8_fp8 v[108:111], v[88:89], v[174:175], v[108:111]
	s_waitcnt vmcnt(8)
	v_mfma_f32_16x16x32_fp8_fp8 v[112:115], v[84:85], v[174:175], v[112:115]
	v_cndmask_b32_e64 v174, 0, v171, s[2:3]
	v_cndmask_b32_e64 v175, 0, v173, s[2:3]
	s_nop 1
	v_mfma_f32_16x16x32_fp8_fp8 v[100:103], v[98:99], v[174:175], v[100:103]
	v_mfma_f32_16x16x32_fp8_fp8 v[104:107], v[94:95], v[174:175], v[104:107]
	v_mfma_f32_16x16x32_fp8_fp8 v[108:111], v[90:91], v[174:175], v[108:111]
	v_mfma_f32_16x16x32_fp8_fp8 v[112:115], v[86:87], v[174:175], v[112:115]
	v_cndmask_b32_e64 v174, 0, 1, s[10:11]
	v_cmp_ne_u32_e64 s[8:9], 1, v174
	s_andn2_b64 vcc, exec, s[10:11]
	s_cbranch_vccnz .LBB0_717
	v_mov_b32_e32 v84, s14
	ds_read_b32 v84, v84 offset:2052
	v_mov_b32_e32 v85, v164
	s_waitcnt lgkmcnt(0)
	v_readfirstlane_b32 s10, v84
	s_ashr_i32 s11, s10, 31
	s_nop 0
	v_writelane_b32 v255, s10, 60
	s_lshl_b64 s[10:11], s[10:11], 12
	s_add_u32 s10, s77, s10
	s_addc_u32 s11, s94, s11
	s_nop 0
	global_load_dwordx4 v[96:99], v85, s[10:11]
	global_load_dwordx4 v[92:95], v85, s[10:11] offset:1024
	global_load_dwordx4 v[88:91], v85, s[10:11] offset:2048
	s_nop 0
	global_load_dwordx4 v[84:87], v85, s[10:11] offset:3072
.LBB0_717:
	v_cndmask_b32_e64 v174, 0, v168, s[4:5]
	v_cndmask_b32_e64 v175, 0, v172, s[4:5]
	s_waitcnt vmcnt(7)
	s_nop 0
	v_mfma_f32_16x16x32_fp8_fp8 v[100:103], v[128:129], v[174:175], v[100:103]
	s_waitcnt vmcnt(6)
	v_mfma_f32_16x16x32_fp8_fp8 v[104:107], v[124:125], v[174:175], v[104:107]
	s_waitcnt vmcnt(5)
	v_mfma_f32_16x16x32_fp8_fp8 v[108:111], v[120:121], v[174:175], v[108:111]
	s_waitcnt vmcnt(4)
	v_mfma_f32_16x16x32_fp8_fp8 v[112:115], v[116:117], v[174:175], v[112:115]
	v_cndmask_b32_e64 v174, 0, v171, s[4:5]
	v_cndmask_b32_e64 v175, 0, v173, s[4:5]
	s_nop 1
	v_mfma_f32_16x16x32_fp8_fp8 v[100:103], v[130:131], v[174:175], v[100:103]
	v_mfma_f32_16x16x32_fp8_fp8 v[104:107], v[126:127], v[174:175], v[104:107]
	v_mfma_f32_16x16x32_fp8_fp8 v[108:111], v[122:123], v[174:175], v[108:111]
	v_mfma_f32_16x16x32_fp8_fp8 v[112:115], v[118:119], v[174:175], v[112:115]
	s_and_b64 vcc, exec, s[8:9]
	s_cbranch_vccnz .LBB0_719
	v_mov_b32_e32 v116, s14
	ds_read_b32 v116, v116 offset:4100
	v_mov_b32_e32 v117, v164
	s_waitcnt lgkmcnt(0)
	v_readfirstlane_b32 s10, v116
	s_ashr_i32 s11, s10, 31
	s_nop 0
	v_writelane_b32 v255, s10, 61
	s_lshl_b64 s[10:11], s[10:11], 12
	s_add_u32 s10, s77, s10
	s_addc_u32 s11, s94, s11
	s_nop 0
	global_load_dwordx4 v[128:131], v117, s[10:11]
	global_load_dwordx4 v[124:127], v117, s[10:11] offset:1024
	global_load_dwordx4 v[120:123], v117, s[10:11] offset:2048
	s_nop 0
	global_load_dwordx4 v[116:119], v117, s[10:11] offset:3072
.LBB0_719:
	v_cndmask_b32_e64 v174, 0, v168, s[6:7]
	v_cndmask_b32_e64 v175, 0, v172, s[6:7]
	v_cndmask_b32_e64 v172, 0, v171, s[6:7]
	v_cndmask_b32_e64 v173, 0, v173, s[6:7]
	s_waitcnt vmcnt(3)
	v_mfma_f32_16x16x32_fp8_fp8 v[100:103], v[144:145], v[174:175], v[100:103]
	s_waitcnt vmcnt(2)
	v_mfma_f32_16x16x32_fp8_fp8 v[104:107], v[140:141], v[174:175], v[104:107]
	s_waitcnt vmcnt(1)
	v_mfma_f32_16x16x32_fp8_fp8 v[108:111], v[136:137], v[174:175], v[108:111]
	s_waitcnt vmcnt(0)
	v_mfma_f32_16x16x32_fp8_fp8 v[112:115], v[132:133], v[174:175], v[112:115]
	v_mfma_f32_16x16x32_fp8_fp8 v[100:103], v[146:147], v[172:173], v[100:103]
	v_mfma_f32_16x16x32_fp8_fp8 v[104:107], v[142:143], v[172:173], v[104:107]
	v_mfma_f32_16x16x32_fp8_fp8 v[108:111], v[138:139], v[172:173], v[108:111]
	v_mfma_f32_16x16x32_fp8_fp8 v[112:115], v[134:135], v[172:173], v[112:115]
	s_and_b64 vcc, exec, s[8:9]
	s_cbranch_vccnz .LBB0_721
	v_mov_b32_e32 v132, s14
	ds_read_b32 v132, v132 offset:6148
	v_mov_b32_e32 v133, v164
	s_waitcnt lgkmcnt(0)
	v_readfirstlane_b32 s8, v132
	s_ashr_i32 s9, s8, 31
	s_nop 0
	v_writelane_b32 v255, s8, 62
	s_lshl_b64 s[8:9], s[8:9], 12
	s_add_u32 s8, s77, s8
	s_addc_u32 s9, s94, s9
	s_nop 0
	global_load_dwordx4 v[144:147], v133, s[8:9]
	global_load_dwordx4 v[140:143], v133, s[8:9] offset:1024
	global_load_dwordx4 v[136:139], v133, s[8:9] offset:2048
	s_nop 0
	global_load_dwordx4 v[132:135], v133, s[8:9] offset:3072
